# final_ln L0 tail: 20 parameter loads issued together up front instead of 11 serialized load-wait-store rounds
# speedup vs baseline: 1.0012x; 1.0012x over previous
.LBB0_1302:
	s_or_b64 exec, exec, s[2:3]
	v_add_u32_e32 v246, 0xfffff000, v102
	v_lshrrev_b32_e32 v246, 11, v246
	v_add_u32_e32 v246, 1, v246
	v_cndmask_b32_e32 v246, 0, v246, vcc
	v_mul_u32_u24_e32 v246, 0x6000, v246
	v_readlane_b32 s98, v253, 26
	v_readlane_b32 s99, v253, 27
	v_add_u32_e32 v247, v246, v64
	v_add_u32_e32 v248, v246, v94
	v_add_u32_e32 v249, v246, v96
	v_add_u32_e32 v251, v246, v98
	s_add_u32 s98, s98, 0x5000
	s_addc_u32 s99, s99, 0
	global_load_dwordx4 v[166:169], v247, s[98:99]
	global_load_dwordx4 v[170:173], v248, s[98:99]
	global_load_dwordx4 v[174:177], v249, s[98:99]
	global_load_dwordx4 v[178:181], v251, s[98:99]
	global_load_dwordx4 v[182:185], v[66:67], off
	global_load_dwordx4 v[198:201], v[68:69], off
	global_load_dwordx4 v[186:189], v[70:71], off
	global_load_dwordx4 v[202:205], v[72:73], off
	global_load_dwordx4 v[190:193], v[74:75], off
	global_load_dwordx4 v[206:209], v[76:77], off
	global_load_dwordx4 v[194:197], v[78:79], off
	global_load_dwordx4 v[210:213], v[80:81], off
	s_add_u32 s98, s98, 0xd000
	s_addc_u32 s99, s99, 0
	global_load_dwordx4 v[214:217], v247, s[98:99]
	global_load_dwordx4 v[218:221], v248, s[98:99]
	global_load_dwordx4 v[222:225], v249, s[98:99]
	global_load_dwordx4 v[226:229], v251, s[98:99]
	s_add_u32 s98, s98, 0x1000
	s_addc_u32 s99, s99, 0
	global_load_dwordx4 v[230:233], v247, s[98:99]
	global_load_dwordx4 v[234:237], v248, s[98:99]
	global_load_dwordx4 v[238:241], v249, s[98:99]
	global_load_dwordx4 v[242:245], v251, s[98:99]
	v_pk_add_f32 v[120:121], v[120:121], v[122:123]
	v_add_u32_e32 v95, 0xfffff000, v102
	v_pk_mul_f32 v[122:123], v[120:121], s[12:13] op_sel_hi:[1,0]
	v_lshrrev_b32_e32 v95, 11, v95
	v_fma_f32 v97, -v123, v123, v122
	v_max_f32_e32 v97, 0, v97
	v_add_u32_e32 v95, 1, v95
	v_add_f32_e32 v97, 0x3727c5ac, v97
	v_cndmask_b32_e32 v95, 0, v95, vcc
	v_cmp_gt_f32_e32 vcc, s18, v97
	v_mul_f32_e32 v99, 0x4b800000, v97
	v_pk_add_f32 v[22:23], v[22:23], v[122:123] op_sel:[0,1] neg_lo:[0,1] neg_hi:[0,1]
	v_cndmask_b32_e32 v97, v97, v99, vcc
	v_rsq_f32_e32 v97, v97
	v_pk_add_f32 v[20:21], v[20:21], v[122:123] op_sel:[0,1] neg_lo:[0,1] neg_hi:[0,1]
	v_pk_add_f32 v[16:17], v[16:17], v[122:123] op_sel:[0,1] neg_lo:[0,1] neg_hi:[0,1]
	v_readlane_b32 s76, v253, 26
	v_mul_f32_e32 v99, 0x45800000, v97
	v_cndmask_b32_e32 v124, v97, v99, vcc
	v_pk_mul_f32 v[22:23], v[22:23], v[124:125] op_sel_hi:[1,0]
	v_pk_mul_f32 v[20:21], v[20:21], v[124:125] op_sel_hi:[1,0]
	s_waitcnt vmcnt(25)
	v_pk_fma_f32 v[58:59], v[58:59], v[22:23], v[62:63]
	v_pk_add_f32 v[22:23], v[28:29], v[122:123] op_sel:[0,1] neg_lo:[0,1] neg_hi:[0,1]
	v_pk_mul_f32 v[16:17], v[16:17], v[124:125] op_sel_hi:[1,0]
	v_pk_mul_f32 v[22:23], v[22:23], v[124:125] op_sel_hi:[1,0]
	v_pk_fma_f32 v[20:21], v[56:57], v[20:21], v[60:61]
	s_waitcnt vmcnt(24)
	v_pk_fma_f32 v[56:57], v[44:45], v[22:23], v[52:53]
	v_pk_add_f32 v[22:23], v[30:31], v[122:123] op_sel:[0,1] neg_lo:[0,1] neg_hi:[0,1]
	s_waitcnt vmcnt(20)
	v_pk_fma_f32 v[36:37], v[16:17], v[32:33], v[36:37]
	v_pk_add_f32 v[16:17], v[18:19], v[122:123] op_sel:[0,1] neg_lo:[0,1] neg_hi:[0,1]
	s_and_b64 s[0:1], exec, s[0:1]
	v_pk_mul_f32 v[22:23], v[22:23], v[124:125] op_sel_hi:[1,0]
	v_pk_mul_f32 v[16:17], v[16:17], v[124:125] op_sel_hi:[1,0]
	v_readlane_b32 s77, v253, 27
	s_or_b64 s[8:9], s[0:1], s[8:9]
	v_pk_fma_f32 v[54:55], v[46:47], v[22:23], v[54:55]
	v_pk_add_f32 v[22:23], v[24:25], v[122:123] op_sel:[0,1] neg_lo:[0,1] neg_hi:[0,1]
	v_pk_fma_f32 v[32:33], v[16:17], v[34:35], v[38:39]
	v_mov_b64_e32 v[16:17], s[76:77]
	s_movk_i32 s0, 0x6000
	v_pk_mul_f32 v[22:23], v[22:23], v[124:125] op_sel_hi:[1,0]
	v_mad_u64_u32 v[16:17], s[0:1], v95, s0, v[16:17]
	v_pk_fma_f32 v[44:45], v[22:23], v[40:41], v[48:49]
	v_pk_add_f32 v[22:23], v[26:27], v[122:123] op_sel:[0,1] neg_lo:[0,1] neg_hi:[0,1]
	s_mov_b64 s[0:1], 0x5000
	v_pk_mul_f32 v[22:23], v[22:23], v[124:125] op_sel_hi:[1,0]
	v_lshl_add_u64 v[18:19], v[16:17], 0, s[0:1]
	v_pk_fma_f32 v[120:121], v[22:23], v[42:43], v[50:51]
	v_lshl_add_u64 v[22:23], v[18:19], 0, v[64:65]
	s_mov_b64 s[0:1], 0x12000
	v_lshl_add_u64 v[28:29], v[16:17], 0, s[0:1]
	v_ashrrev_i32_e32 v103, 31, v102
	s_mov_b64 s[0:1], 0x13000
	v_mov_b32_e32 v95, v65
	v_lshl_add_u64 v[24:25], v[16:17], 0, s[0:1]
	v_lshlrev_b64 v[16:17], 12, v[102:103]
	v_lshl_add_u64 v[34:35], v[18:19], 0, v[94:95]
	v_mov_b32_e32 v97, v65
	v_mov_b32_e32 v99, v65
	v_lshl_add_u64 v[30:31], v[90:91], 0, v[16:17]
	v_lshl_add_u64 v[128:129], v[18:19], 0, v[96:97]
	v_lshl_add_u64 v[122:123], v[18:19], 0, v[98:99]
	v_lshl_add_u64 v[50:51], v[28:29], 0, v[94:95]
	v_lshl_add_u64 v[42:43], v[24:25], 0, v[94:95]
	v_lshl_add_u64 v[46:47], v[28:29], 0, v[64:65]
	v_readlane_b32 s78, v253, 28
	v_readlane_b32 s79, v253, 29
	v_readlane_b32 s80, v253, 30
	v_readlane_b32 s81, v253, 31
	v_readlane_b32 s82, v253, 32
	v_readlane_b32 s83, v253, 33
	v_readlane_b32 s84, v253, 34
	v_readlane_b32 s85, v253, 35
	v_readlane_b32 s86, v253, 36
	v_readlane_b32 s87, v253, 37
	v_readlane_b32 s88, v253, 38
	v_readlane_b32 s89, v253, 39
	v_readlane_b32 s90, v253, 40
	v_readlane_b32 s91, v253, 41
	s_waitcnt vmcnt(16)
	v_pk_mul_f32 v[16:17], v[118:119], v[166:167]
	s_nop 0
	v_pk_fma_f32 v[48:49], v[20:21], s[14:15], v[16:17] op_sel_hi:[1,0,1]
	v_pk_mul_f32 v[26:27], v[116:117], v[168:169]
	v_pk_fma_f32 v[52:53], v[58:59], s[14:15], v[26:27] op_sel_hi:[1,0,1]
	v_add_f32_e32 v26, v48, v49
	v_add_f32_e32 v26, v26, v52
	v_add_f32_e32 v26, v26, v53
	v_add_f32_e32 v38, 0, v26
	v_pk_mul_f32 v[60:61], v[48:49], v[48:49]
	v_lshlrev_b64 v[26:27], 11, v[102:103]
	v_pk_mul_f32 v[62:63], v[52:53], v[52:53]
	v_add_f32_e32 v60, v60, v61
	v_add_f32_e32 v60, v60, v62
	v_add_f32_e32 v60, v60, v63
	v_lshl_add_u64 v[40:41], v[24:25], 0, v[64:65]
	v_lshl_add_u64 v[26:27], v[92:93], 0, v[26:27]
	v_pk_mul_f32 v[34:35], v[114:115], v[170:171]
	v_pk_fma_f32 v[58:59], v[56:57], s[14:15], v[34:35] op_sel_hi:[1,0,1]
	v_pk_mul_f32 v[34:35], v[112:113], v[172:173]
	v_pk_mul_f32 v[102:103], v[58:59], v[58:59]
	v_pk_fma_f32 v[56:57], v[54:55], s[14:15], v[34:35] op_sel_hi:[1,0,1]
	v_add_f32_e32 v34, v58, v59
	v_add_f32_e32 v34, v34, v56
	v_add_f32_e32 v34, v34, v57
	v_add_f32_e32 v38, v38, v34
	v_pk_mul_f32 v[112:113], v[56:57], v[56:57]
	v_add_f32_e32 v102, v102, v103
	v_add_f32_e32 v102, v102, v112
	v_add_f32_e32 v102, v102, v113
	v_add_f32_e32 v60, v60, v102
	v_mov_b32_e32 v102, v100
	v_pk_mul_f32 v[34:35], v[110:111], v[174:175]
	s_nop 0
	v_pk_fma_f32 v[54:55], v[44:45], s[14:15], v[34:35] op_sel_hi:[1,0,1]
	v_pk_mul_f32 v[34:35], v[108:109], v[176:177]
	v_pk_mul_f32 v[110:111], v[54:55], v[54:55]
	v_pk_fma_f32 v[44:45], v[120:121], s[14:15], v[34:35] op_sel_hi:[1,0,1]
	v_add_f32_e32 v34, v54, v55
	v_pk_mul_f32 v[108:109], v[44:45], v[44:45]
	v_add_f32_e32 v61, v110, v111
	v_add_f32_e32 v34, v34, v44
	v_add_f32_e32 v61, v61, v108
	v_add_f32_e32 v34, v34, v45
	v_add_f32_e32 v61, v61, v109
	v_add_f32_e32 v95, v38, v34
	v_lshl_add_u64 v[38:39], v[28:29], 0, v[96:97]
	v_lshl_add_u64 v[34:35], v[24:25], 0, v[96:97]
	v_add_f32_e32 v60, v60, v61
	v_lshl_add_u64 v[24:25], v[24:25], 0, v[98:99]
	v_pk_mul_f32 v[106:107], v[106:107], v[178:179]
	s_nop 0
	v_pk_fma_f32 v[36:37], v[36:37], s[14:15], v[106:107] op_sel_hi:[1,0,1]
	v_pk_mul_f32 v[104:105], v[104:105], v[180:181]
	v_pk_mul_f32 v[106:107], v[36:37], v[36:37]
	v_pk_fma_f32 v[32:33], v[32:33], s[14:15], v[104:105] op_sel_hi:[1,0,1]
	v_add_f32_e32 v97, v36, v37
	v_pk_mul_f32 v[104:105], v[32:33], v[32:33]
	v_add_f32_e32 v61, v106, v107
	v_add_f32_e32 v97, v97, v32
	v_add_f32_e32 v61, v61, v104
	v_add_f32_e32 v97, v97, v33
	v_add_f32_e32 v61, v61, v105
	v_add_f32_e32 v60, v60, v61
	v_add_f32_e32 v61, v95, v97
	v_mov_b32_e32 v97, v132
	v_add_f32_dpp v60, v60, v60 row_ror:8 row_mask:0xf bank_mask:0xf bound_ctrl:1
	v_add_f32_dpp v61, v61, v61 row_ror:8 row_mask:0xf bank_mask:0xf bound_ctrl:1
	v_mov_b32_e32 v95, v101
	v_add_f32_dpp v60, v60, v60 row_ror:4 row_mask:0xf bank_mask:0xf bound_ctrl:1
	v_add_f32_dpp v61, v61, v61 row_ror:4 row_mask:0xf bank_mask:0xf bound_ctrl:1
	s_nop 0
	v_add_f32_dpp v60, v60, v60 row_ror:2 row_mask:0xf bank_mask:0xf bound_ctrl:1
	v_add_f32_dpp v61, v61, v61 row_ror:2 row_mask:0xf bank_mask:0xf bound_ctrl:1
	s_nop 0
	v_add_f32_dpp v60, v60, v60 row_ror:1 row_mask:0xf bank_mask:0xf bound_ctrl:1
	v_add_f32_dpp v61, v61, v61 row_ror:1 row_mask:0xf bank_mask:0xf bound_ctrl:1
	v_mov_b32_e32 v62, v61
	s_nop 1
	v_permlane16_swap_b32_e32 v61, v62
	v_add_f32_e32 v61, v61, v62
	v_mov_b32_e32 v62, v60
	s_nop 1
	v_permlane16_swap_b32_e32 v60, v62
	v_add_f32_e32 v60, v60, v62
	v_mov_b32_e32 v63, v61
	v_mov_b32_e32 v62, v60
	s_nop 0
	v_permlane32_swap_b32_e32 v61, v63
	v_permlane32_swap_b32_e32 v60, v62
	v_pk_add_f32 v[60:61], v[60:61], v[62:63]
	s_nop 0
	v_pk_mul_f32 v[60:61], v[60:61], s[12:13] op_sel_hi:[1,0]
	s_nop 0
	v_fma_f32 v62, -v61, v61, v60
	v_max_f32_e32 v62, 0, v62
	v_add_f32_e32 v62, 0x3727c5ac, v62
	v_cmp_gt_f32_e32 vcc, s18, v62
	v_mul_f32_e32 v63, 0x4b800000, v62
	v_pk_add_f32 v[48:49], v[48:49], v[60:61] op_sel:[0,1] neg_lo:[0,1] neg_hi:[0,1]
	v_cndmask_b32_e32 v62, v62, v63, vcc
	v_rsq_f32_e32 v62, v62
	s_nop 0
	v_mul_f32_e32 v63, 0x45800000, v62
	v_cndmask_b32_e32 v62, v62, v63, vcc
	v_pk_mul_f32 v[48:49], v[48:49], v[62:63] op_sel_hi:[1,0]
	s_nop 0
	s_waitcnt vmcnt(0)
	v_pk_fma_f32 v[16:17], v[182:183], v[48:49], v[198:199]
	v_pk_add_f32 v[20:21], v[52:53], v[60:61] op_sel:[0,1] neg_lo:[0,1] neg_hi:[0,1]
	s_nop 0
	v_pk_mul_f32 v[20:21], v[20:21], v[62:63] op_sel_hi:[1,0]
	s_nop 0
	v_pk_fma_f32 v[18:19], v[184:185], v[20:21], v[200:201]
	global_store_dwordx4 v[30:31], v[16:19], off
	s_nop 1
	s_nop 0
	v_pk_add_f32 v[40:41], v[230:231], 1.0 op_sel_hi:[1,0]
	s_nop 0
	v_pk_fma_f32 v[16:17], v[16:17], v[40:41], v[214:215]
	v_pk_add_f32 v[20:21], v[232:233], 1.0 op_sel_hi:[1,0]
	v_cvt_pk_bf16_f32 v16, v16, v17
	v_pk_fma_f32 v[18:19], v[18:19], v[20:21], v[216:217]
	v_pk_add_f32 v[40:41], v[58:59], v[60:61] op_sel:[0,1] neg_lo:[0,1] neg_hi:[0,1]
	v_cvt_pk_bf16_f32 v17, v18, v19
	global_store_dwordx2 v[26:27], v[16:17], off
	s_nop 0
	v_pk_mul_f32 v[40:41], v[40:41], v[62:63] op_sel_hi:[1,0]
	v_pk_fma_f32 v[16:17], v[40:41], v[186:187], v[202:203]
	v_pk_add_f32 v[20:21], v[56:57], v[60:61] op_sel:[0,1] neg_lo:[0,1] neg_hi:[0,1]
	s_nop 0
	v_pk_mul_f32 v[20:21], v[20:21], v[62:63] op_sel_hi:[1,0]
	s_nop 0
	v_pk_fma_f32 v[18:19], v[20:21], v[188:189], v[204:205]
	global_store_dwordx4 v[30:31], v[16:19], off offset:1024
	s_nop 1
	s_nop 0
	v_pk_add_f32 v[40:41], v[234:235], 1.0 op_sel_hi:[1,0]
	s_nop 0
	v_pk_fma_f32 v[16:17], v[16:17], v[40:41], v[218:219]
	v_pk_add_f32 v[20:21], v[236:237], 1.0 op_sel_hi:[1,0]
	v_cvt_pk_bf16_f32 v16, v16, v17
	v_pk_fma_f32 v[18:19], v[18:19], v[20:21], v[220:221]
	v_pk_add_f32 v[40:41], v[54:55], v[60:61] op_sel:[0,1] neg_lo:[0,1] neg_hi:[0,1]
	v_cvt_pk_bf16_f32 v17, v18, v19
	global_store_dwordx2 v[26:27], v[16:17], off offset:512
	s_nop 0
	v_pk_mul_f32 v[40:41], v[40:41], v[62:63] op_sel_hi:[1,0]
	v_pk_fma_f32 v[16:17], v[40:41], v[190:191], v[206:207]
	v_pk_add_f32 v[20:21], v[44:45], v[60:61] op_sel:[0,1] neg_lo:[0,1] neg_hi:[0,1]
	s_nop 0
	v_pk_mul_f32 v[20:21], v[20:21], v[62:63] op_sel_hi:[1,0]
	s_nop 0
	v_pk_fma_f32 v[18:19], v[20:21], v[192:193], v[208:209]
	global_store_dwordx4 v[30:31], v[16:19], off offset:2048
	s_nop 1
	s_nop 0
	v_pk_add_f32 v[34:35], v[238:239], 1.0 op_sel_hi:[1,0]
	s_nop 0
	v_pk_fma_f32 v[16:17], v[16:17], v[34:35], v[222:223]
	v_pk_add_f32 v[20:21], v[240:241], 1.0 op_sel_hi:[1,0]
	v_cvt_pk_bf16_f32 v16, v16, v17
	v_pk_fma_f32 v[18:19], v[18:19], v[20:21], v[224:225]
	v_pk_add_f32 v[34:35], v[36:37], v[60:61] op_sel:[0,1] neg_lo:[0,1] neg_hi:[0,1]
	v_cvt_pk_bf16_f32 v17, v18, v19
	global_store_dwordx2 v[26:27], v[16:17], off offset:1024
	s_nop 0
	v_pk_mul_f32 v[34:35], v[34:35], v[62:63] op_sel_hi:[1,0]
	v_pk_fma_f32 v[16:17], v[34:35], v[194:195], v[210:211]
	v_pk_add_f32 v[20:21], v[32:33], v[60:61] op_sel:[0,1] neg_lo:[0,1] neg_hi:[0,1]
	s_nop 0
	v_pk_mul_f32 v[20:21], v[20:21], v[62:63] op_sel_hi:[1,0]
	s_nop 0
	v_pk_fma_f32 v[18:19], v[20:21], v[196:197], v[212:213]
	global_store_dwordx4 v[30:31], v[16:19], off offset:3072
	s_nop 1
	v_lshl_add_u64 v[20:21], v[28:29], 0, v[98:99]
	s_nop 0
	v_pk_add_f32 v[24:25], v[242:243], 1.0 op_sel_hi:[1,0]
	s_nop 0
	v_pk_fma_f32 v[16:17], v[16:17], v[24:25], v[226:227]
	v_pk_add_f32 v[20:21], v[244:245], 1.0 op_sel_hi:[1,0]
	v_cvt_pk_bf16_f32 v16, v16, v17
	v_pk_fma_f32 v[18:19], v[18:19], v[20:21], v[228:229]
	v_mov_b64_e32 v[20:21], v[4:5]
	v_cvt_pk_bf16_f32 v17, v18, v19
	global_store_dwordx2 v[26:27], v[16:17], off offset:1536
	v_mov_b64_e32 v[22:23], v[6:7]
	v_mov_b64_e32 v[28:29], v[8:9]
	v_mov_b64_e32 v[30:31], v[10:11]
	v_mov_b64_e32 v[24:25], v[12:13]
	v_mov_b64_e32 v[26:27], v[14:15]
	v_mov_b64_e32 v[16:17], v[0:1]
	v_mov_b64_e32 v[18:19], v[2:3]
	s_andn2_b64 exec, exec, s[8:9]
	s_cbranch_execz .LBB0_1312
